# attention output tail: half-wave column groups exchanged with v_permlane32_swap, 4 dwordx4 stores instead of 8 dwordx2; packed 1/sum scaling
# baseline (speedup 1.0000x reference)
.LBB0_351:
	v_cndmask_b32_e64 v1, v50, v151, s[4:5]
	v_cndmask_b32_e64 v200, v1, v50, s[8:9]
	v_max3_f32 v1, v111, v66, v156
	v_max3_f32 v1, v1, v155, v154
	v_max3_f32 v1, v1, v153, v152
	v_max3_f32 v1, v1, v117, v115
	v_max3_f32 v1, v1, v74, v73
	v_max3_f32 v1, v1, v72, v71
	v_max3_f32 v1, v1, v70, v69
	v_max3_f32 v1, v1, v68, v67
	v_max3_f32 v1, v1, v34, v35
	v_max3_f32 v1, v1, v36, v37
	v_max3_f32 v1, v1, v38, v39
	v_max3_f32 v1, v1, v40, v41
	v_max3_f32 v1, v1, v42, v43
	v_max3_f32 v1, v1, v44, v45
	v_max3_f32 v1, v1, v46, v47
	v_max3_f32 v1, v1, v48, v49
	v_max3_f32 v1, v1, v18, v19
	v_max3_f32 v1, v1, v20, v21
	v_max3_f32 v1, v1, v22, v23
	v_max3_f32 v1, v1, v24, v25
	v_max3_f32 v1, v1, v26, v27
	v_max3_f32 v1, v1, v28, v29
	v_max3_f32 v1, v1, v30, v31
	v_max3_f32 v1, v1, v32, v33
	v_max3_f32 v1, v1, v2, v3
	v_max3_f32 v1, v1, v4, v5
	v_max3_f32 v1, v1, v6, v7
	v_max3_f32 v1, v1, v8, v9
	v_max3_f32 v1, v1, v10, v11
	v_max3_f32 v1, v1, v12, v13
	v_max3_f32 v1, v1, v14, v15
	v_cndmask_b32_e64 v199, v151, v51, s[8:9]
	v_max3_f32 v1, v1, v16, v17
	v_cndmask_b32_e64 v198, v52, v151, s[10:11]
	v_cndmask_b32_e64 v197, v53, v151, s[12:13]
	v_max3_f32 v1, v1, v200, v199
	v_cndmask_b32_e64 v196, v54, v151, s[14:15]
	v_cndmask_b32_e64 v195, v55, v151, s[16:17]
	v_max3_f32 v1, v1, v198, v197
	v_cndmask_b32_e64 v194, v56, v151, s[18:19]
	v_cndmask_b32_e64 v193, v57, v151, s[20:21]
	v_max3_f32 v1, v1, v196, v195
	v_cndmask_b32_e64 v192, v58, v151, s[22:23]
	v_cndmask_b32_e64 v191, v59, v151, s[24:25]
	v_max3_f32 v1, v1, v194, v193
	v_cndmask_b32_e64 v190, v60, v151, s[26:27]
	v_cndmask_b32_e64 v189, v61, v151, s[28:29]
	v_max3_f32 v1, v1, v192, v191
	v_cndmask_b32_e64 v188, v62, v151, s[30:31]
	v_cndmask_b32_e64 v187, v63, v151, s[34:35]
	v_max3_f32 v1, v1, v190, v189
	v_cndmask_b32_e64 v186, v64, v151, s[36:37]
	v_cndmask_b32_e64 v185, v65, v151, s[38:39]
	v_max3_f32 v1, v1, v188, v187
	v_max3_f32 v1, v1, v186, v185
	ds_bpermute_b32 v50, v135, v1
	s_or_b32 s46, s48, 16
	s_waitcnt lgkmcnt(0)
	v_max_f32_e32 v50, v50, v50
	v_max_f32_e32 v201, v1, v50
	v_sub_f32_e32 v1, v66, v201
	v_exp_f32_e32 v50, v1
	v_sub_f32_e32 v51, v156, v201
	v_exp_f32_e32 v52, v51
	v_sub_f32_e32 v51, v155, v201
	v_exp_f32_e32 v55, v51
	v_sub_f32_e32 v51, v154, v201
	v_exp_f32_e32 v64, v51
	v_sub_f32_e32 v51, v153, v201
	v_add_f32_e32 v1, 0, v50
	v_exp_f32_e32 v78, v51
	v_sub_f32_e32 v51, v152, v201
	v_add_f32_e32 v1, v52, v1
	v_exp_f32_e32 v153, v51
	v_sub_f32_e32 v51, v117, v201
	v_add_f32_e32 v1, v55, v1
	v_exp_f32_e32 v156, v51
	v_sub_f32_e32 v51, v115, v201
	v_add_f32_e32 v1, v64, v1
	v_exp_f32_e32 v166, v51
	v_sub_f32_e32 v51, v74, v201
	v_add_f32_e32 v1, v78, v1
	v_exp_f32_e32 v51, v51
	v_sub_f32_e32 v53, v73, v201
	v_add_f32_e32 v1, v153, v1
	v_exp_f32_e32 v56, v53
	v_sub_f32_e32 v53, v72, v201
	v_add_f32_e32 v1, v156, v1
	v_exp_f32_e32 v63, v53
	v_sub_f32_e32 v53, v71, v201
	v_add_f32_e32 v1, v166, v1
	v_exp_f32_e32 v71, v53
	v_sub_f32_e32 v53, v70, v201
	v_add_f32_e32 v1, v51, v1
	v_exp_f32_e32 v117, v53
	v_sub_f32_e32 v53, v69, v201
	v_add_f32_e32 v1, v56, v1
	v_exp_f32_e32 v157, v53
	v_sub_f32_e32 v53, v68, v201
	v_add_f32_e32 v1, v63, v1
	v_exp_f32_e32 v165, v53
	v_sub_f32_e32 v53, v67, v201
	v_add_f32_e32 v1, v71, v1
	v_exp_f32_e32 v176, v53
	v_sub_f32_e32 v34, v34, v201
	v_add_f32_e32 v1, v117, v1
	v_exp_f32_e32 v53, v34
	v_sub_f32_e32 v34, v35, v201
	v_add_f32_e32 v1, v157, v1
	v_exp_f32_e32 v58, v34
	v_sub_f32_e32 v34, v36, v201
	v_add_f32_e32 v1, v165, v1
	v_exp_f32_e32 v66, v34
	v_sub_f32_e32 v34, v37, v201
	v_add_f32_e32 v1, v176, v1
	v_exp_f32_e32 v73, v34
	v_sub_f32_e32 v34, v38, v201
	v_add_f32_e32 v1, v53, v1
	v_exp_f32_e32 v154, v34
	v_sub_f32_e32 v34, v39, v201
	v_add_f32_e32 v1, v58, v1
	v_exp_f32_e32 v160, v34
	v_sub_f32_e32 v34, v40, v201
	v_add_f32_e32 v1, v66, v1
	v_exp_f32_e32 v168, v34
	v_sub_f32_e32 v34, v41, v201
	v_add_f32_e32 v1, v73, v1
	v_exp_f32_e32 v178, v34
	v_sub_f32_e32 v34, v42, v201
	v_add_f32_e32 v1, v154, v1
	v_exp_f32_e32 v54, v34
	v_sub_f32_e32 v34, v43, v201
	v_add_f32_e32 v1, v160, v1
	v_exp_f32_e32 v61, v34
	v_sub_f32_e32 v34, v44, v201
	v_add_f32_e32 v1, v168, v1
	v_exp_f32_e32 v69, v34
	v_sub_f32_e32 v34, v45, v201
	v_add_f32_e32 v1, v178, v1
	v_exp_f32_e32 v76, v34
	v_sub_f32_e32 v34, v46, v201
	v_add_f32_e32 v1, v54, v1
	v_exp_f32_e32 v155, v34
	v_sub_f32_e32 v34, v47, v201
	v_add_f32_e32 v1, v61, v1
	v_exp_f32_e32 v163, v34
	v_sub_f32_e32 v34, v48, v201
	v_add_f32_e32 v1, v69, v1
	v_exp_f32_e32 v173, v34
	v_sub_f32_e32 v34, v49, v201
	v_add_f32_e32 v1, v76, v1
	v_exp_f32_e32 v180, v34
	v_sub_f32_e32 v18, v18, v201
	v_add_f32_e32 v1, v155, v1
	v_exp_f32_e32 v49, v18
	v_sub_f32_e32 v18, v19, v201
	v_add_f32_e32 v1, v163, v1
	v_exp_f32_e32 v65, v18
	v_sub_f32_e32 v18, v20, v201
	v_add_f32_e32 v1, v173, v1
	v_exp_f32_e32 v72, v18
	v_sub_f32_e32 v18, v21, v201
	v_add_f32_e32 v1, v180, v1
	v_exp_f32_e32 v79, v18
	v_sub_f32_e32 v18, v22, v201
	v_add_f32_e32 v1, v49, v1
	v_exp_f32_e32 v158, v18
	v_sub_f32_e32 v18, v23, v201
	v_add_f32_e32 v1, v65, v1
	v_exp_f32_e32 v167, v18
	v_sub_f32_e32 v18, v24, v201
	v_add_f32_e32 v1, v72, v1
	v_exp_f32_e32 v177, v18
	v_sub_f32_e32 v18, v25, v201
	v_add_f32_e32 v1, v79, v1
	v_exp_f32_e32 v182, v18
	v_sub_f32_e32 v18, v26, v201
	v_add_f32_e32 v1, v158, v1
	v_exp_f32_e32 v59, v18
	v_sub_f32_e32 v18, v27, v201
	v_add_f32_e32 v1, v167, v1
	v_exp_f32_e32 v68, v18
	v_sub_f32_e32 v18, v28, v201
	v_add_f32_e32 v1, v177, v1
	v_exp_f32_e32 v75, v18
	v_sub_f32_e32 v18, v29, v201
	v_add_f32_e32 v1, v182, v1
	v_exp_f32_e32 v81, v18
	v_sub_f32_e32 v18, v30, v201
	v_add_f32_e32 v1, v59, v1
	v_exp_f32_e32 v161, v18
	v_sub_f32_e32 v18, v31, v201
	v_add_f32_e32 v1, v68, v1
	v_exp_f32_e32 v171, v18
	v_sub_f32_e32 v18, v32, v201
	v_add_f32_e32 v1, v75, v1
	v_exp_f32_e32 v179, v18
	v_sub_f32_e32 v18, v33, v201
	v_add_f32_e32 v1, v81, v1
	v_exp_f32_e32 v183, v18
	v_sub_f32_e32 v2, v2, v201
	v_add_f32_e32 v1, v161, v1
	v_exp_f32_e32 v62, v2
	v_sub_f32_e32 v2, v3, v201
	v_add_f32_e32 v1, v171, v1
	v_exp_f32_e32 v70, v2
	v_sub_f32_e32 v2, v4, v201
	v_add_f32_e32 v1, v179, v1
	v_exp_f32_e32 v77, v2
	v_sub_f32_e32 v2, v5, v201
	v_add_f32_e32 v1, v183, v1
	v_exp_f32_e32 v115, v2
	v_sub_f32_e32 v2, v6, v201
	v_add_f32_e32 v1, v62, v1
	v_exp_f32_e32 v164, v2
	v_sub_f32_e32 v2, v7, v201
	v_add_f32_e32 v1, v70, v1
	v_exp_f32_e32 v174, v2
	v_sub_f32_e32 v2, v8, v201
	v_add_f32_e32 v1, v77, v1
	v_exp_f32_e32 v181, v2
	v_sub_f32_e32 v2, v9, v201
	v_add_f32_e32 v1, v115, v1
	v_exp_f32_e32 v184, v2
	v_sub_f32_e32 v2, v10, v201
	v_add_f32_e32 v1, v164, v1
	v_exp_f32_e32 v67, v2
	v_sub_f32_e32 v2, v11, v201
	v_add_f32_e32 v1, v174, v1
	v_exp_f32_e32 v74, v2
	v_sub_f32_e32 v2, v12, v201
	v_add_f32_e32 v1, v181, v1
	v_exp_f32_e32 v80, v2
	v_sub_f32_e32 v2, v13, v201
	v_add_f32_e32 v1, v184, v1
	v_exp_f32_e32 v152, v2
	v_sub_f32_e32 v2, v14, v201
	v_add_f32_e32 v1, v67, v1
	v_exp_f32_e32 v159, v2
	v_sub_f32_e32 v2, v15, v201
	v_add_f32_e32 v1, v74, v1
	v_exp_f32_e32 v162, v2
	v_sub_f32_e32 v2, v16, v201
	v_add_f32_e32 v1, v80, v1
	v_exp_f32_e32 v169, v2
	v_sub_f32_e32 v2, v17, v201
	v_add_f32_e32 v1, v152, v1
	v_exp_f32_e32 v175, v2
	v_sub_f32_e32 v2, v200, v201
	v_add_f32_e32 v1, v159, v1
	v_exp_f32_e32 v43, v2
	v_sub_f32_e32 v2, v199, v201
	v_add_f32_e32 v1, v162, v1
	v_exp_f32_e32 v44, v2
	v_sub_f32_e32 v2, v198, v201
	v_add_f32_e32 v1, v169, v1
	v_exp_f32_e32 v45, v2
	v_sub_f32_e32 v2, v197, v201
	v_add_f32_e32 v1, v175, v1
	v_exp_f32_e32 v46, v2
	v_sub_f32_e32 v2, v196, v201
	v_add_f32_e32 v1, v43, v1
	v_exp_f32_e32 v47, v2
	v_sub_f32_e32 v2, v195, v201
	v_add_f32_e32 v1, v44, v1
	v_exp_f32_e32 v48, v2
	v_sub_f32_e32 v2, v194, v201
	v_add_f32_e32 v1, v45, v1
	v_exp_f32_e32 v57, v2
	v_sub_f32_e32 v2, v193, v201
	v_add_f32_e32 v1, v46, v1
	v_exp_f32_e32 v60, v2
	v_sub_f32_e32 v2, v192, v201
	v_add_f32_e32 v1, v47, v1
	v_exp_f32_e32 v35, v2
	v_sub_f32_e32 v2, v191, v201
	v_add_f32_e32 v1, v48, v1
	v_exp_f32_e32 v36, v2
	v_sub_f32_e32 v2, v190, v201
	v_add_f32_e32 v1, v57, v1
	v_exp_f32_e32 v37, v2
	v_sub_f32_e32 v2, v189, v201
	v_add_f32_e32 v1, v60, v1
	v_exp_f32_e32 v38, v2
	v_sub_f32_e32 v2, v188, v201
	v_add_f32_e32 v1, v35, v1
	v_exp_f32_e32 v39, v2
	v_sub_f32_e32 v2, v187, v201
	v_add_f32_e32 v1, v36, v1
	v_exp_f32_e32 v40, v2
	v_sub_f32_e32 v2, v186, v201
	v_add_f32_e32 v1, v37, v1
	v_exp_f32_e32 v41, v2
	v_sub_f32_e32 v2, v185, v201
	v_add_f32_e32 v1, v38, v1
	v_exp_f32_e32 v42, v2
	v_add_f32_e32 v1, v39, v1
	v_add_f32_e32 v1, v40, v1
	v_add_f32_e32 v1, v41, v1
	v_add_f32_e32 v1, v42, v1
	ds_bpermute_b32 v2, v135, v1
	v_lshl_add_u32 v22, v113, 1, v126
	v_cvt_pk_bf16_f32 v18, v50, v52
	v_cvt_pk_bf16_f32 v19, v55, v64
	v_cvt_pk_bf16_f32 v20, v78, v153
	s_waitcnt lgkmcnt(0)
	v_add_f32_e32 v1, v1, v2
	v_sub_f32_e32 v2, v111, v201
	v_exp_f32_e32 v2, v2
	v_cvt_pk_bf16_f32 v21, v156, v166
	v_or_b32_e32 v50, s46, v125
	v_lshl_add_u32 v50, v50, 1, v126
	v_add_f32_e32 v34, v2, v1
	v_or_b32_e32 v1, s48, v125
	v_lshl_add_u32 v1, v1, 1, v126
	ds_read_b64 v[2:3], v22 offset:36864
	ds_read_b64 v[4:5], v1 offset:36864
	ds_read_b64 v[22:23], v22 offset:53504
	ds_read_b64 v[24:25], v1 offset:53504
	v_or_b32_e32 v1, s46, v124
	v_lshl_add_u32 v1, v1, 1, v126
	v_cvt_pk_bf16_f32 v186, v51, v56
	v_cvt_pk_bf16_f32 v187, v63, v71
	v_cvt_pk_bf16_f32 v188, v117, v157
	v_cvt_pk_bf16_f32 v189, v165, v176
	ds_read_b64 v[190:191], v1 offset:36864
	ds_read_b64 v[192:193], v50 offset:36864
	s_waitcnt lgkmcnt(4)
	v_mfma_f32_32x32x16_bf16 v[2:17], v[2:5], v[18:21], 0
	s_add_i32 s46, s78, s91
	v_or_b32_e32 v55, s46, v125
	v_lshl_add_u32 v55, v55, 1, v126
	s_waitcnt lgkmcnt(2)
	v_mfma_f32_32x32x16_bf16 v[18:33], v[22:25], v[18:21], 0
	s_waitcnt lgkmcnt(0)
	v_mfma_f32_32x32x16_bf16 v[2:17], v[190:193], v[186:189], v[2:17]
	ds_read_b64 v[190:191], v1 offset:53504
	ds_read_b64 v[192:193], v50 offset:53504
	v_or_b32_e32 v1, s46, v124
	v_lshl_add_u32 v1, v1, 1, v126
	v_cvt_pk_bf16_f32 v50, v53, v58
	v_cvt_pk_bf16_f32 v51, v66, v73
	v_cvt_pk_bf16_f32 v52, v154, v160
	v_cvt_pk_bf16_f32 v53, v168, v178
	s_waitcnt lgkmcnt(0)
	v_mfma_f32_32x32x16_bf16 v[18:33], v[190:193], v[186:189], v[18:33]
	ds_read_b64 v[186:187], v1 offset:36864
	ds_read_b64 v[188:189], v55 offset:36864
	s_or_b32 s46, s46, 16
	s_waitcnt lgkmcnt(0)
	v_mfma_f32_32x32x16_bf16 v[2:17], v[186:189], v[50:53], v[2:17]
	ds_read_b64 v[186:187], v1 offset:53504
	ds_read_b64 v[188:189], v55 offset:53504
	v_or_b32_e32 v1, s46, v124
	v_lshl_add_u32 v1, v1, 1, v126
	s_waitcnt lgkmcnt(0)
	v_mfma_f32_32x32x16_bf16 v[18:33], v[186:189], v[50:53], v[18:33]
	v_cvt_pk_bf16_f32 v50, v54, v61
	v_or_b32_e32 v54, s46, v125
	v_lshl_add_u32 v54, v54, 1, v126
	v_cvt_pk_bf16_f32 v51, v69, v76
	v_cvt_pk_bf16_f32 v52, v155, v163
	v_cvt_pk_bf16_f32 v53, v173, v180
	ds_read_b64 v[154:155], v1 offset:36864
	ds_read_b64 v[156:157], v54 offset:36864
	s_waitcnt lgkmcnt(0)
	v_mfma_f32_32x32x16_bf16 v[2:17], v[154:157], v[50:53], v[2:17]
	ds_read_b64 v[154:155], v1 offset:53504
	ds_read_b64 v[156:157], v54 offset:53504
	s_or_b32 s46, s91, s76
	v_or_b32_e32 v1, s46, v124
	v_lshl_add_u32 v1, v1, 1, v126
	s_waitcnt lgkmcnt(0)
	v_mfma_f32_32x32x16_bf16 v[18:33], v[154:157], v[50:53], v[18:33]
	v_cvt_pk_bf16_f32 v50, v49, v65
	v_or_b32_e32 v49, s46, v125
	v_lshl_add_u32 v49, v49, 1, v126
	v_cvt_pk_bf16_f32 v51, v72, v79
	v_cvt_pk_bf16_f32 v52, v158, v167
	v_cvt_pk_bf16_f32 v53, v177, v182
	ds_read_b64 v[154:155], v1 offset:36864
	ds_read_b64 v[156:157], v49 offset:36864
	s_waitcnt lgkmcnt(0)
	v_mfma_f32_32x32x16_bf16 v[2:17], v[154:157], v[50:53], v[2:17]
	ds_read_b64 v[154:155], v1 offset:53504
	ds_read_b64 v[156:157], v49 offset:53504
	s_or_b32 s46, s46, 16
	v_or_b32_e32 v1, s46, v124
	v_or_b32_e32 v49, s46, v125
	v_lshl_add_u32 v1, v1, 1, v126
	v_lshl_add_u32 v49, v49, 1, v126
	s_add_i32 s46, s77, s91
	s_waitcnt lgkmcnt(0)
	v_mfma_f32_32x32x16_bf16 v[18:33], v[154:157], v[50:53], v[18:33]
	v_cvt_pk_bf16_f32 v50, v59, v68
	v_cvt_pk_bf16_f32 v51, v75, v81
	v_cvt_pk_bf16_f32 v52, v161, v171
	v_cvt_pk_bf16_f32 v53, v179, v183
	ds_read_b64 v[154:155], v1 offset:36864
	ds_read_b64 v[156:157], v49 offset:36864
	s_mov_b32 s91, 32
	s_waitcnt lgkmcnt(0)
	v_mfma_f32_32x32x16_bf16 v[2:17], v[154:157], v[50:53], v[2:17]
	ds_read_b64 v[154:155], v1 offset:53504
	ds_read_b64 v[156:157], v49 offset:53504
	v_or_b32_e32 v1, s46, v124
	v_or_b32_e32 v49, s46, v125
	v_lshl_add_u32 v1, v1, 1, v126
	v_lshl_add_u32 v49, v49, 1, v126
	s_or_b32 s46, s46, 16
	s_waitcnt lgkmcnt(0)
	v_mfma_f32_32x32x16_bf16 v[18:33], v[154:157], v[50:53], v[18:33]
	v_cvt_pk_bf16_f32 v50, v62, v70
	v_cvt_pk_bf16_f32 v51, v77, v115
	v_cvt_pk_bf16_f32 v52, v164, v174
	v_cvt_pk_bf16_f32 v53, v181, v184
	ds_read_b64 v[62:63], v1 offset:36864
	ds_read_b64 v[64:65], v49 offset:36864
	s_waitcnt lgkmcnt(0)
	v_mfma_f32_32x32x16_bf16 v[2:17], v[62:65], v[50:53], v[2:17]
	ds_read_b64 v[62:63], v1 offset:53504
	ds_read_b64 v[64:65], v49 offset:53504
	v_or_b32_e32 v1, s46, v124
	v_or_b32_e32 v49, s46, v125
	v_lshl_add_u32 v1, v1, 1, v126
	v_lshl_add_u32 v49, v49, 1, v126
	s_or_b32 s46, s48, 0x80
	s_waitcnt lgkmcnt(0)
	v_mfma_f32_32x32x16_bf16 v[18:33], v[62:65], v[50:53], v[18:33]
	v_cvt_pk_bf16_f32 v50, v67, v74
	v_cvt_pk_bf16_f32 v51, v80, v152
	v_cvt_pk_bf16_f32 v52, v159, v162
	v_cvt_pk_bf16_f32 v53, v169, v175
	ds_read_b64 v[62:63], v1 offset:36864
	ds_read_b64 v[64:65], v49 offset:36864
	s_waitcnt lgkmcnt(0)
	v_mfma_f32_32x32x16_bf16 v[2:17], v[62:65], v[50:53], v[2:17]
	ds_read_b64 v[62:63], v1 offset:53504
	ds_read_b64 v[64:65], v49 offset:53504
	v_cvt_pk_bf16_f32 v44, v43, v44
	v_or_b32_e32 v1, s46, v124
	v_or_b32_e32 v43, s46, v125
	v_lshl_add_u32 v1, v1, 1, v126
	v_lshl_add_u32 v43, v43, 1, v126
	v_cvt_pk_bf16_f32 v45, v45, v46
	s_waitcnt lgkmcnt(0)
	v_mfma_f32_32x32x16_bf16 v[18:33], v[62:65], v[50:53], v[18:33]
	v_cvt_pk_bf16_f32 v46, v47, v48
	v_cvt_pk_bf16_f32 v47, v57, v60
	ds_read_b64 v[48:49], v1 offset:36864
	ds_read_b64 v[50:51], v43 offset:36864
	s_or_b32 s46, s48, 0x90
	s_waitcnt lgkmcnt(0)
	v_mfma_f32_32x32x16_bf16 v[2:17], v[48:51], v[44:47], v[2:17]
	ds_read_b64 v[48:49], v1 offset:53504
	ds_read_b64 v[50:51], v43 offset:53504
	v_cvt_pk_bf16_f32 v36, v35, v36
	v_or_b32_e32 v1, s46, v124
	v_or_b32_e32 v35, s46, v125
	v_lshl_add_u32 v1, v1, 1, v126
	v_lshl_add_u32 v35, v35, 1, v126
	v_cvt_pk_bf16_f32 v37, v37, v38
	v_cvt_pk_bf16_f32 v38, v39, v40
	v_cvt_pk_bf16_f32 v39, v41, v42
	ds_read_b64 v[40:41], v1 offset:36864
	ds_read_b64 v[42:43], v35 offset:36864
	s_waitcnt lgkmcnt(2)
	v_mfma_f32_32x32x16_bf16 v[18:33], v[48:51], v[44:47], v[18:33]
	s_waitcnt lgkmcnt(0)
	v_mfma_f32_32x32x16_bf16 v[2:17], v[40:43], v[36:39], v[2:17]
	ds_read_b64 v[40:41], v1 offset:53504
	ds_read_b64 v[42:43], v35 offset:53504
	v_div_scale_f32 v1, s[46:47], v34, v34, 1.0
	v_rcp_f32_e32 v35, v1
	s_mov_b64 s[46:47], 0
	s_waitcnt lgkmcnt(0)
	v_mfma_f32_32x32x16_bf16 v[18:33], v[40:43], v[36:39], v[18:33]
	v_fma_f32 v36, -v1, v35, 1.0
	v_fmac_f32_e32 v35, v36, v35
	v_div_scale_f32 v36, vcc, 1.0, v34, 1.0
	v_mul_f32_e32 v37, v36, v35
	v_fma_f32 v38, -v1, v37, v36
	v_fmac_f32_e32 v37, v38, v35
	v_fma_f32 v1, -v1, v37, v36
	v_div_fmas_f32 v1, v1, v35, v37
	v_div_fixup_f32 v1, v1, v34, 1.0
	v_or_b32_e32 v34, s48, v109
	v_ashrrev_i32_e32 v35, 31, v34
	v_lshlrev_b64 v[34:35], 11, v[34:35]
	v_lshl_add_u64 v[34:35], v[118:119], 0, v[34:35]
	v_mbcnt_lo_u32_b32 v38, -1, 0
	v_mbcnt_hi_u32_b32 v38, -1, v38
	v_and_b32_e32 v38, 32, v38
	v_lshrrev_b32_e32 v38, 2, v38
	v_mov_b32_e32 v39, 0
	v_lshl_add_u64 v[34:35], v[34:35], 0, v[38:39]
	v_pk_mul_f32 v[2:3], v[2:3], v[0:1] op_sel:[0,1] op_sel_hi:[1,1]
	v_pk_mul_f32 v[4:5], v[4:5], v[0:1] op_sel:[0,1] op_sel_hi:[1,1]
	v_pk_mul_f32 v[6:7], v[6:7], v[0:1] op_sel:[0,1] op_sel_hi:[1,1]
	v_pk_mul_f32 v[8:9], v[8:9], v[0:1] op_sel:[0,1] op_sel_hi:[1,1]
	v_pk_mul_f32 v[10:11], v[10:11], v[0:1] op_sel:[0,1] op_sel_hi:[1,1]
	v_pk_mul_f32 v[12:13], v[12:13], v[0:1] op_sel:[0,1] op_sel_hi:[1,1]
	v_pk_mul_f32 v[14:15], v[14:15], v[0:1] op_sel:[0,1] op_sel_hi:[1,1]
	v_pk_mul_f32 v[16:17], v[16:17], v[0:1] op_sel:[0,1] op_sel_hi:[1,1]
	v_pk_mul_f32 v[18:19], v[18:19], v[0:1] op_sel:[0,1] op_sel_hi:[1,1]
	v_pk_mul_f32 v[20:21], v[20:21], v[0:1] op_sel:[0,1] op_sel_hi:[1,1]
	v_pk_mul_f32 v[22:23], v[22:23], v[0:1] op_sel:[0,1] op_sel_hi:[1,1]
	v_pk_mul_f32 v[24:25], v[24:25], v[0:1] op_sel:[0,1] op_sel_hi:[1,1]
	v_pk_mul_f32 v[26:27], v[26:27], v[0:1] op_sel:[0,1] op_sel_hi:[1,1]
	v_pk_mul_f32 v[28:29], v[28:29], v[0:1] op_sel:[0,1] op_sel_hi:[1,1]
	v_pk_mul_f32 v[30:31], v[30:31], v[0:1] op_sel:[0,1] op_sel_hi:[1,1]
	v_pk_mul_f32 v[32:33], v[32:33], v[0:1] op_sel:[0,1] op_sel_hi:[1,1]
	v_cvt_pk_bf16_f32 v2, v2, v3
	v_cvt_pk_bf16_f32 v3, v4, v5
	v_cvt_pk_bf16_f32 v4, v6, v7
	v_cvt_pk_bf16_f32 v5, v8, v9
	v_cvt_pk_bf16_f32 v6, v10, v11
	v_cvt_pk_bf16_f32 v7, v12, v13
	v_cvt_pk_bf16_f32 v8, v14, v15
	v_cvt_pk_bf16_f32 v9, v16, v17
	v_cvt_pk_bf16_f32 v10, v18, v19
	v_cvt_pk_bf16_f32 v11, v20, v21
	v_cvt_pk_bf16_f32 v12, v22, v23
	v_cvt_pk_bf16_f32 v13, v24, v25
	v_cvt_pk_bf16_f32 v14, v26, v27
	v_cvt_pk_bf16_f32 v15, v28, v29
	v_cvt_pk_bf16_f32 v16, v30, v31
	v_cvt_pk_bf16_f32 v17, v32, v33
	s_nop 1
	v_permlane32_swap_b32 v2, v4
	v_permlane32_swap_b32 v3, v5
	v_permlane32_swap_b32 v6, v8
	v_permlane32_swap_b32 v7, v9
	v_permlane32_swap_b32 v10, v12
	v_permlane32_swap_b32 v11, v13
	v_permlane32_swap_b32 v14, v16
	v_permlane32_swap_b32 v15, v17
	global_store_dwordx4 v[34:35], v[2:5], off
	global_store_dwordx4 v[34:35], v[6:9], off offset:32
	global_store_dwordx4 v[34:35], v[10:13], off offset:64
	global_store_dwordx4 v[34:35], v[14:17], off offset:96
	s_waitcnt vmcnt(4)
	v_mov_b64_e32 v[2:3], v[82:83]
	v_mov_b64_e32 v[6:7], v[86:87]
	v_mov_b64_e32 v[10:11], v[90:91]
	v_mov_b64_e32 v[14:15], v[94:95]
	s_and_b64 vcc, exec, s[74:75]
	v_mov_b64_e32 v[4:5], v[84:85]
	v_mov_b64_e32 v[8:9], v[88:89]
	v_mov_b64_e32 v[12:13], v[92:93]
	v_mov_b64_e32 v[16:17], v[96:97]
	s_cbranch_vccnz .LBB0_328
